# GEMM K loop without any s_setprio (A/B of the per-segment priority flips; everything else as v23)
# speedup vs baseline: 1.0067x; 1.0067x over previous
; #define PG8_STAGE(bufoff, gbase, voff) do { _Pragma("unroll") for (int _i = 0; _i < 2; ++_i) \
;         __builtin_amdgcn_global_load_lds((const unsigned*)((const char*)(gbase) + (voff)[_i]), (PG8_LAS unsigned*)(lds + (bufoff) + ldsw + _i * 8192), 16, 0, 0); } while (0)
; #define PG8_LDA(dst, b, h) do { _Pragma("unroll") for (int m = 0; m < 4; ++m) _Pragma("unroll") for (int k = 0; k < 2; ++k) dst[m][k] = *(const PG8_LAS bf16x8*)(lds + PG8_SA(b, h) + aoff + m * 2048 + k * 1024); } while (0)
; #define PG8_LDB(dst, b, h) do { _Pragma("unroll") for (int n = 0; n < 2; ++n) _Pragma("unroll") for (int k = 0; k < 2; ++k) dst[n][k] = *(const PG8_LAS bf16x8*)(lds + PG8_SB(b, h) + boff + n * 2048 + k * 1024); } while (0)
; #define PG8_WAIT_V(n) asm volatile("s_waitcnt vmcnt(" #n ")" ::: "memory")
; #define PG8_WAIT_L(n) asm volatile("s_waitcnt lgkmcnt(" #n ")" ::: "memory")
; #define PG8_BAR __builtin_amdgcn_s_barrier()
; #define PG8_SCHED __builtin_amdgcn_sched_barrier(0)
; template <class Epi, class Sched, bool ALIGN_EPI = false, bool SP2 = false>
; __device__ __forceinline__ void gemm_phase(PG8_LAS unsigned char* lds, const Gemm g, const Sched& S, const Epi& E) {
;     ...
;         const char* nA = has_next ? (const char*)g.A + (size_t)nxt.pm * tstep : cA; const char* nB = has_next ? (const char*)g.Bt + (size_t)nxt.pn * tstep : cB;
;         for (int t = 0; t < nt; t += 2) {
;             const bool last = (t == nt - 2);
;             const char* a1 = cA + (size_t)(t + 1) * kstep;
;             const char* a2 = last ? nA : cA + (size_t)(t + 2) * kstep; const char* b2 = last ? nB : cB + (size_t)(t + 2) * kstep;
;             const char* a3 = a2 + kstep; const char* b3 = b2 + kstep;
;             if (last && has_next) S.a_ready(nxt);
;             if constexpr (SP2) {
;             PG8_LDB(B0, 0, 0); PG8_LDB(B1, 0, 1); PG8_SCHED; PG8_LDA(At, 0, 0); PG8_STAGE(PG8_SA(1, 1), a1 + hstep, voffA);
;             PG8_WAIT_V(8); PG8_WAIT_L(0); PG8_BAR; PG8_MMA(0, 0, At, B0); PG8_MMA(0, 1, At, B1); PG8_BAR; PG8_SCHED;
;             PG8_LDA(At, 0, 1); PG8_STAGE(PG8_SB(0, 0), b2, voffB); PG8_STAGE(PG8_SB(0, 1), b2 + hstep, voffB); PG8_STAGE(PG8_SA(0, 0), a2, voffA);
;             PG8_WAIT_V(8); PG8_WAIT_L(0); PG8_BAR; PG8_MMA(1, 0, At, B0); PG8_MMA(1, 1, At, B1); PG8_BAR; PG8_SCHED;
.LBB0_321:
	s_add_u32 s12, s16, 0x80
	s_addc_u32 s13, s17, 0
	s_add_u32 s16, s14, 0x100
	s_addc_u32 s17, s15, 0
	s_mov_b32 s14, 0
	s_nop 0
	s_nop 0
	s_waitcnt lgkmcnt(0)
	s_add_i32 s42, s14, 2
	s_add_u32 s43, s12, 0x80
	s_addc_u32 s15, s13, 0
	s_add_i32 s75, 0, 0x10000
	s_cmp_eq_u32 s25, s14
	s_cselect_b32 s15, s55, s15
	s_cselect_b32 s14, s54, s43
	s_cselect_b32 vcc_hi, s65, s17
	s_cselect_b32 vcc_lo, s64, s16
	s_add_i32 s43, 0, 0x14000
	v_add_u32_e32 v142, s75, v199
	v_add_u32_e32 v178, s43, v199
	ds_read_b128 v[130:133], v142
	ds_read_b128 v[134:137], v142 offset:1024
	ds_read_b128 v[138:141], v142 offset:2048
	ds_read_b128 v[142:145], v142 offset:3072
	ds_read_b128 v[170:173], v178
	ds_read_b128 v[174:177], v178 offset:1024
	ds_read_b128 v[202:205], v178 offset:2048
	ds_read_b128 v[206:209], v178 offset:3072
	v_lshl_add_u64 v[178:179], s[12:13], 0, v[166:167]
	s_add_i32 m0, s56, 0xc000
	ds_read_b128 v[210:213], v201
	ds_read_b128 v[214:217], v201 offset:1024
	ds_read_b128 v[218:221], v201 offset:2048
	ds_read_b128 v[222:225], v201 offset:3072
	ds_read_b128 v[226:229], v201 offset:4096
	ds_read_b128 v[230:233], v201 offset:5120
	ds_read_b128 v[234:237], v201 offset:6144
	ds_read_b128 v[238:241], v201 offset:7168
	global_load_lds_dwordx4 v[178:179], off
	v_lshl_add_u64 v[178:179], s[12:13], 0, v[168:169]
	s_add_i32 m0, s56, 0xe000
	s_nop 0
	global_load_lds_dwordx4 v[178:179], off
	s_waitcnt vmcnt(8)
	s_waitcnt lgkmcnt(0)
	s_barrier
	s_waitcnt lgkmcnt(0)
	v_mfma_f32_16x16x32_bf16 v[126:129], v[130:133], v[210:213], 0
	v_mfma_f32_16x16x32_bf16 v[126:129], v[134:137], v[214:217], v[126:129]
	v_mfma_f32_16x16x32_bf16 v[122:125], v[138:141], v[210:213], 0
	v_mfma_f32_16x16x32_bf16 v[122:125], v[142:145], v[214:217], v[122:125]
	v_mfma_f32_16x16x32_bf16 v[110:113], v[130:133], v[218:221], 0
	v_mfma_f32_16x16x32_bf16 v[110:113], v[134:137], v[222:225], v[110:113]
	v_mfma_f32_16x16x32_bf16 v[106:109], v[138:141], v[218:221], 0
	v_mfma_f32_16x16x32_bf16 v[106:109], v[142:145], v[222:225], v[106:109]
	v_mfma_f32_16x16x32_bf16 v[94:97], v[130:133], v[226:229], 0
	v_mfma_f32_16x16x32_bf16 v[94:97], v[134:137], v[230:233], v[94:97]
	v_mfma_f32_16x16x32_bf16 v[90:93], v[138:141], v[226:229], 0
	v_mfma_f32_16x16x32_bf16 v[90:93], v[142:145], v[230:233], v[90:93]
	v_mfma_f32_16x16x32_bf16 v[78:81], v[130:133], v[234:237], 0
	v_mfma_f32_16x16x32_bf16 v[78:81], v[134:137], v[238:241], v[78:81]
	v_mfma_f32_16x16x32_bf16 v[74:77], v[138:141], v[234:237], 0
	v_mfma_f32_16x16x32_bf16 v[74:77], v[142:145], v[238:241], v[74:77]
	v_mfma_f32_16x16x32_bf16 v[118:121], v[170:173], v[210:213], 0
	v_mfma_f32_16x16x32_bf16 v[118:121], v[174:177], v[214:217], v[118:121]
	v_mfma_f32_16x16x32_bf16 v[114:117], v[202:205], v[210:213], 0
	v_mfma_f32_16x16x32_bf16 v[114:117], v[206:209], v[214:217], v[114:117]
	v_mfma_f32_16x16x32_bf16 v[102:105], v[170:173], v[218:221], 0
	v_mfma_f32_16x16x32_bf16 v[102:105], v[174:177], v[222:225], v[102:105]
	v_mfma_f32_16x16x32_bf16 v[98:101], v[202:205], v[218:221], 0
	v_mfma_f32_16x16x32_bf16 v[98:101], v[206:209], v[222:225], v[98:101]
	v_mfma_f32_16x16x32_bf16 v[86:89], v[170:173], v[226:229], 0
	v_mfma_f32_16x16x32_bf16 v[86:89], v[174:177], v[230:233], v[86:89]
	v_mfma_f32_16x16x32_bf16 v[82:85], v[202:205], v[226:229], 0
	v_mfma_f32_16x16x32_bf16 v[82:85], v[206:209], v[230:233], v[82:85]
	v_mfma_f32_16x16x32_bf16 v[70:73], v[170:173], v[234:237], 0
	v_mfma_f32_16x16x32_bf16 v[70:73], v[174:177], v[238:241], v[70:73]
	v_mfma_f32_16x16x32_bf16 v[66:69], v[202:205], v[234:237], 0
	v_mfma_f32_16x16x32_bf16 v[66:69], v[206:209], v[238:241], v[66:69]
	s_barrier
	s_add_i32 s75, s75, s23
	v_lshl_add_u64 v[178:179], vcc, 0, v[0:1]
	s_mov_b32 m0, s75
	ds_read_b128 v[210:213], v201 offset:16384
	ds_read_b128 v[214:217], v201 offset:17408
	ds_read_b128 v[218:221], v201 offset:18432
	ds_read_b128 v[222:225], v201 offset:19456
	ds_read_b128 v[226:229], v201 offset:20480
	ds_read_b128 v[230:233], v201 offset:21504
	ds_read_b128 v[234:237], v201 offset:22528
	ds_read_b128 v[238:241], v201 offset:23552
	global_load_lds_dwordx4 v[178:179], off
	s_add_i32 m0, s75, 0x2000
	v_lshl_add_u64 v[242:243], vcc, 0, v[162:163]
	s_add_u32 vcc_lo, vcc_lo, s84
	s_addc_u32 vcc_hi, vcc_hi, 0
	s_add_i32 s43, s43, s23
	global_load_lds_dwordx4 v[242:243], off
	v_lshl_add_u64 v[244:245], vcc, 0, v[0:1]
	s_mov_b32 m0, s43
	v_lshl_add_u64 v[246:247], vcc, 0, v[162:163]
	global_load_lds_dwordx4 v[244:245], off
	s_add_i32 m0, s43, 0x2000
	v_lshl_add_u64 v[248:249], s[14:15], 0, v[158:159]
	global_load_lds_dwordx4 v[246:247], off
	s_mov_b32 m0, s56
	v_lshl_add_u64 v[250:251], s[14:15], 0, v[160:161]
	global_load_lds_dwordx4 v[248:249], off
	s_mov_b32 m0, s82
	s_nop 0
	global_load_lds_dwordx4 v[250:251], off
	s_waitcnt vmcnt(8)
	s_waitcnt lgkmcnt(0)
	s_barrier
; #define PG8_STAGE(bufoff, gbase, voff) do { _Pragma("unroll") for (int _i = 0; _i < 2; ++_i) \
;         __builtin_amdgcn_global_load_lds((const unsigned*)((const char*)(gbase) + (voff)[_i]), (PG8_LAS unsigned*)(lds + (bufoff) + ldsw + _i * 8192), 16, 0, 0); } while (0)
; #define PG8_LDA(dst, b, h) do { _Pragma("unroll") for (int m = 0; m < 4; ++m) _Pragma("unroll") for (int k = 0; k < 2; ++k) dst[m][k] = *(const PG8_LAS bf16x8*)(lds + PG8_SA(b, h) + aoff + m * 2048 + k * 1024); } while (0)
; #define PG8_LDB(dst, b, h) do { _Pragma("unroll") for (int n = 0; n < 2; ++n) _Pragma("unroll") for (int k = 0; k < 2; ++k) dst[n][k] = *(const PG8_LAS bf16x8*)(lds + PG8_SB(b, h) + boff + n * 2048 + k * 1024); } while (0)
; #define PG8_MMA(ai, bj, At, Bt) do { __builtin_amdgcn_s_setprio(1); _Pragma("unroll") for (int m = 0; m < 4; ++m) _Pragma("unroll") for (int n = 0; n < 2; ++n) _Pragma("unroll") for (int k = 0; k < 2; ++k) \
;         acc[ai][bj][m][n] = __builtin_amdgcn_mfma_f32_16x16x32_bf16(Bt[n][k], At[m][k], acc[ai][bj][m][n], 0, 0, 0); __builtin_amdgcn_s_setprio(0); } while (0)
; #define PG8_WAIT_V(n) asm volatile("s_waitcnt vmcnt(" #n ")" ::: "memory")
; #define PG8_WAIT_L(n) asm volatile("s_waitcnt lgkmcnt(" #n ")" ::: "memory")
; #define PG8_BAR __builtin_amdgcn_s_barrier()
; #define PG8_SCHED __builtin_amdgcn_sched_barrier(0)
; template <class Epi, class Sched, bool ALIGN_EPI = false, bool SP2 = false>
; __device__ __forceinline__ void gemm_phase(PG8_LAS unsigned char* lds, const Gemm g, const Sched& S, const Epi& E) {
;     ...
;             PG8_WAIT_V(8); PG8_WAIT_L(0); PG8_BAR; PG8_MMA(1, 0, At, B0); PG8_MMA(1, 1, At, B1); PG8_BAR; PG8_SCHED;
;             PG8_LDB(B0, 1, 0); PG8_LDB(B1, 1, 1); PG8_SCHED; PG8_LDA(At, 1, 0); PG8_STAGE(PG8_SA(0, 1), a2 + hstep, voffA);
;             PG8_WAIT_V(8); PG8_WAIT_L(0); PG8_BAR; PG8_MMA(0, 0, At, B0); PG8_MMA(0, 1, At, B1); PG8_BAR; PG8_SCHED;
	s_waitcnt lgkmcnt(0)
	v_mfma_f32_16x16x32_bf16 v[62:65], v[130:133], v[210:213], 0
	v_mfma_f32_16x16x32_bf16 v[62:65], v[134:137], v[214:217], v[62:65]
	v_mfma_f32_16x16x32_bf16 v[58:61], v[138:141], v[210:213], 0
	v_mfma_f32_16x16x32_bf16 v[58:61], v[142:145], v[214:217], v[58:61]
	v_mfma_f32_16x16x32_bf16 v[46:49], v[130:133], v[218:221], 0
	v_mfma_f32_16x16x32_bf16 v[46:49], v[134:137], v[222:225], v[46:49]
	v_mfma_f32_16x16x32_bf16 v[42:45], v[138:141], v[218:221], 0
	v_mfma_f32_16x16x32_bf16 v[42:45], v[142:145], v[222:225], v[42:45]
	v_mfma_f32_16x16x32_bf16 v[30:33], v[130:133], v[226:229], 0
	v_mfma_f32_16x16x32_bf16 v[30:33], v[134:137], v[230:233], v[30:33]
	v_mfma_f32_16x16x32_bf16 v[26:29], v[138:141], v[226:229], 0
	v_mfma_f32_16x16x32_bf16 v[26:29], v[142:145], v[230:233], v[26:29]
	v_mfma_f32_16x16x32_bf16 v[14:17], v[130:133], v[234:237], 0
	v_mfma_f32_16x16x32_bf16 v[14:17], v[134:137], v[238:241], v[14:17]
	v_mfma_f32_16x16x32_bf16 v[10:13], v[138:141], v[234:237], 0
	v_mfma_f32_16x16x32_bf16 v[10:13], v[142:145], v[238:241], v[10:13]
	v_mfma_f32_16x16x32_bf16 v[54:57], v[170:173], v[210:213], 0
	v_mfma_f32_16x16x32_bf16 v[54:57], v[174:177], v[214:217], v[54:57]
	v_mfma_f32_16x16x32_bf16 v[50:53], v[202:205], v[210:213], 0
	v_mfma_f32_16x16x32_bf16 v[50:53], v[206:209], v[214:217], v[50:53]
	v_mfma_f32_16x16x32_bf16 v[38:41], v[170:173], v[218:221], 0
	v_mfma_f32_16x16x32_bf16 v[38:41], v[174:177], v[222:225], v[38:41]
	v_mfma_f32_16x16x32_bf16 v[34:37], v[202:205], v[218:221], 0
	v_mfma_f32_16x16x32_bf16 v[34:37], v[206:209], v[222:225], v[34:37]
	v_mfma_f32_16x16x32_bf16 v[22:25], v[170:173], v[226:229], 0
	v_mfma_f32_16x16x32_bf16 v[22:25], v[174:177], v[230:233], v[22:25]
	v_mfma_f32_16x16x32_bf16 v[18:21], v[202:205], v[226:229], 0
	v_mfma_f32_16x16x32_bf16 v[18:21], v[206:209], v[230:233], v[18:21]
	v_mfma_f32_16x16x32_bf16 v[6:9], v[170:173], v[234:237], 0
	v_mfma_f32_16x16x32_bf16 v[6:9], v[174:177], v[238:241], v[6:9]
	v_mfma_f32_16x16x32_bf16 v[2:5], v[202:205], v[234:237], 0
	v_mfma_f32_16x16x32_bf16 v[2:5], v[206:209], v[238:241], v[2:5]
	s_barrier
	s_add_i32 s43, 0, 0x18000
	s_add_i32 s75, 0, 0x1c000
	v_add_u32_e32 v142, s43, v199
	v_add_u32_e32 v206, s75, v199
	ds_read_b128 v[130:133], v142
	ds_read_b128 v[134:137], v142 offset:1024
	ds_read_b128 v[138:141], v142 offset:2048
	ds_read_b128 v[142:145], v142 offset:3072
	ds_read_b128 v[170:173], v206
	ds_read_b128 v[174:177], v206 offset:1024
	ds_read_b128 v[202:205], v206 offset:2048
	ds_read_b128 v[206:209], v206 offset:3072
	s_add_u32 s14, s14, s84
	s_addc_u32 s15, s15, 0
	s_mov_b32 m0, s83
	v_lshl_add_u64 v[252:253], s[14:15], 0, v[158:159]
	ds_read_b128 v[210:213], v201 offset:32768
	ds_read_b128 v[214:217], v201 offset:33792
	ds_read_b128 v[218:221], v201 offset:34816
	ds_read_b128 v[222:225], v201 offset:35840
	ds_read_b128 v[226:229], v201 offset:36864
	ds_read_b128 v[230:233], v201 offset:37888
	ds_read_b128 v[234:237], v201 offset:38912
	ds_read_b128 v[238:241], v201 offset:39936
	global_load_lds_dwordx4 v[252:253], off
	v_lshl_add_u64 v[252:253], s[14:15], 0, v[160:161]
	s_mov_b32 m0, s24
	s_nop 0
	global_load_lds_dwordx4 v[252:253], off
	s_waitcnt vmcnt(8)
	s_waitcnt lgkmcnt(0)
	s_barrier
	s_waitcnt lgkmcnt(0)
	v_mfma_f32_16x16x32_bf16 v[126:129], v[130:133], v[210:213], v[126:129]
	v_mfma_f32_16x16x32_bf16 v[126:129], v[134:137], v[214:217], v[126:129]
	v_mfma_f32_16x16x32_bf16 v[122:125], v[138:141], v[210:213], v[122:125]
	v_mfma_f32_16x16x32_bf16 v[122:125], v[142:145], v[214:217], v[122:125]
	v_mfma_f32_16x16x32_bf16 v[110:113], v[130:133], v[218:221], v[110:113]
	v_mfma_f32_16x16x32_bf16 v[110:113], v[134:137], v[222:225], v[110:113]
	v_mfma_f32_16x16x32_bf16 v[106:109], v[138:141], v[218:221], v[106:109]
	v_mfma_f32_16x16x32_bf16 v[106:109], v[142:145], v[222:225], v[106:109]
	v_mfma_f32_16x16x32_bf16 v[94:97], v[130:133], v[226:229], v[94:97]
	v_mfma_f32_16x16x32_bf16 v[94:97], v[134:137], v[230:233], v[94:97]
	v_mfma_f32_16x16x32_bf16 v[90:93], v[138:141], v[226:229], v[90:93]
	v_mfma_f32_16x16x32_bf16 v[90:93], v[142:145], v[230:233], v[90:93]
	v_mfma_f32_16x16x32_bf16 v[78:81], v[130:133], v[234:237], v[78:81]
	v_mfma_f32_16x16x32_bf16 v[78:81], v[134:137], v[238:241], v[78:81]
	v_mfma_f32_16x16x32_bf16 v[74:77], v[138:141], v[234:237], v[74:77]
	v_mfma_f32_16x16x32_bf16 v[74:77], v[142:145], v[238:241], v[74:77]
	v_mfma_f32_16x16x32_bf16 v[118:121], v[170:173], v[210:213], v[118:121]
	v_mfma_f32_16x16x32_bf16 v[118:121], v[174:177], v[214:217], v[118:121]
	v_mfma_f32_16x16x32_bf16 v[114:117], v[202:205], v[210:213], v[114:117]
	v_mfma_f32_16x16x32_bf16 v[114:117], v[206:209], v[214:217], v[114:117]
	v_mfma_f32_16x16x32_bf16 v[102:105], v[170:173], v[218:221], v[102:105]
	v_mfma_f32_16x16x32_bf16 v[102:105], v[174:177], v[222:225], v[102:105]
	v_mfma_f32_16x16x32_bf16 v[98:101], v[202:205], v[218:221], v[98:101]
	v_mfma_f32_16x16x32_bf16 v[98:101], v[206:209], v[222:225], v[98:101]
	v_mfma_f32_16x16x32_bf16 v[86:89], v[170:173], v[226:229], v[86:89]
	v_mfma_f32_16x16x32_bf16 v[86:89], v[174:177], v[230:233], v[86:89]
	v_mfma_f32_16x16x32_bf16 v[82:85], v[202:205], v[226:229], v[82:85]
	v_mfma_f32_16x16x32_bf16 v[82:85], v[206:209], v[230:233], v[82:85]
	v_mfma_f32_16x16x32_bf16 v[70:73], v[170:173], v[234:237], v[70:73]
	v_mfma_f32_16x16x32_bf16 v[70:73], v[174:177], v[238:241], v[70:73]
	v_mfma_f32_16x16x32_bf16 v[66:69], v[202:205], v[234:237], v[66:69]
	v_mfma_f32_16x16x32_bf16 v[66:69], v[206:209], v[238:241], v[66:69]
	s_barrier
; #define PG8_STAGE(bufoff, gbase, voff) do { _Pragma("unroll") for (int _i = 0; _i < 2; ++_i) \
;         __builtin_amdgcn_global_load_lds((const unsigned*)((const char*)(gbase) + (voff)[_i]), (PG8_LAS unsigned*)(lds + (bufoff) + ldsw + _i * 8192), 16, 0, 0); } while (0)
; #define PG8_LDA(dst, b, h) do { _Pragma("unroll") for (int m = 0; m < 4; ++m) _Pragma("unroll") for (int k = 0; k < 2; ++k) dst[m][k] = *(const PG8_LAS bf16x8*)(lds + PG8_SA(b, h) + aoff + m * 2048 + k * 1024); } while (0)
; #define PG8_LDB(dst, b, h) do { _Pragma("unroll") for (int n = 0; n < 2; ++n) _Pragma("unroll") for (int k = 0; k < 2; ++k) dst[n][k] = *(const PG8_LAS bf16x8*)(lds + PG8_SB(b, h) + boff + n * 2048 + k * 1024); } while (0)
; template <class Epi, class Sched, bool ALIGN_EPI = false, bool SP2 = false>
; __device__ __forceinline__ void gemm_phase(PG8_LAS unsigned char* lds, const Gemm g, const Sched& S, const Epi& E) {
;     ...
;         for (int t = 0; t < nt; t += 2) {
;             const bool last = (t == nt - 2);
;             const char* a1 = cA + (size_t)(t + 1) * kstep;
;             const char* a2 = last ? nA : cA + (size_t)(t + 2) * kstep; const char* b2 = last ? nB : cB + (size_t)(t + 2) * kstep;
;             const char* a3 = a2 + kstep; const char* b3 = b2 + kstep;
;             if (last && has_next) S.a_ready(nxt);
;             if constexpr (SP2) {
;             PG8_LDB(B0, 0, 0); PG8_LDB(B1, 0, 1); PG8_SCHED; PG8_LDA(At, 0, 0); PG8_STAGE(PG8_SA(1, 1), a1 + hstep, voffA);
;             PG8_WAIT_V(8); PG8_WAIT_L(0); PG8_BAR; PG8_MMA(0, 0, At, B0); PG8_MMA(0, 1, At, B1); PG8_BAR; PG8_SCHED;
;             PG8_LDA(At, 0, 1); PG8_STAGE(PG8_SB(0, 0), b2, voffB); PG8_STAGE(PG8_SB(0, 1), b2 + hstep, voffB); PG8_STAGE(PG8_SA(0, 0), a2, voffA);
;             PG8_WAIT_V(8); PG8_WAIT_L(0); PG8_BAR; PG8_MMA(1, 0, At, B0); PG8_MMA(1, 1, At, B1); PG8_BAR; PG8_SCHED;
;             PG8_LDB(B0, 1, 0); PG8_LDB(B1, 1, 1); PG8_SCHED; PG8_LDA(At, 1, 0); PG8_STAGE(PG8_SA(0, 1), a2 + hstep, voffA);
;             PG8_WAIT_V(8); PG8_WAIT_L(0); PG8_BAR; PG8_MMA(0, 0, At, B0); PG8_MMA(0, 1, At, B1); PG8_BAR; PG8_SCHED;
;             PG8_LDA(At, 1, 1); PG8_STAGE(PG8_SB(1, 0), b3, voffB); PG8_STAGE(PG8_SB(1, 1), b3 + hstep, voffB); PG8_STAGE(PG8_SA(1, 0), a3, voffA);
;             PG8_WAIT_V(8); PG8_WAIT_L(0); PG8_BAR; PG8_MMA(1, 0, At, B0); PG8_MMA(1, 1, At, B1); PG8_BAR; PG8_SCHED;
	s_add_i32 s14, s43, s23
	v_lshl_add_u64 v[178:179], v[178:179], 0, s[94:95]
	s_mov_b32 m0, s14
	ds_read_b128 v[210:213], v201 offset:49152
	ds_read_b128 v[214:217], v201 offset:50176
	ds_read_b128 v[218:221], v201 offset:51200
	ds_read_b128 v[222:225], v201 offset:52224
	ds_read_b128 v[226:229], v201 offset:53248
	ds_read_b128 v[230:233], v201 offset:54272
	ds_read_b128 v[234:237], v201 offset:55296
	ds_read_b128 v[238:241], v201 offset:56320
	global_load_lds_dwordx4 v[178:179], off
	v_lshl_add_u64 v[178:179], v[242:243], 0, s[94:95]
	s_add_i32 m0, s14, 0x2000
	s_add_i32 s14, s75, s23
	global_load_lds_dwordx4 v[178:179], off
	v_lshl_add_u64 v[178:179], v[244:245], 0, s[94:95]
	s_mov_b32 m0, s14
	s_nop 0
	global_load_lds_dwordx4 v[178:179], off
	v_lshl_add_u64 v[178:179], v[246:247], 0, s[94:95]
	s_add_i32 m0, s14, 0x2000
	s_nop 0
	global_load_lds_dwordx4 v[178:179], off
	v_lshl_add_u64 v[178:179], v[248:249], 0, s[94:95]
	s_mov_b32 m0, s63
	s_nop 0
	global_load_lds_dwordx4 v[178:179], off
	v_lshl_add_u64 v[178:179], v[250:251], 0, s[94:95]
	s_mov_b32 m0, s70
	s_nop 0
	global_load_lds_dwordx4 v[178:179], off
	s_waitcnt vmcnt(8)
	s_waitcnt lgkmcnt(0)
	s_barrier
	s_waitcnt lgkmcnt(0)
	v_mfma_f32_16x16x32_bf16 v[62:65], v[130:133], v[210:213], v[62:65]
	v_mfma_f32_16x16x32_bf16 v[62:65], v[134:137], v[214:217], v[62:65]
	v_mfma_f32_16x16x32_bf16 v[58:61], v[138:141], v[210:213], v[58:61]
	v_mfma_f32_16x16x32_bf16 v[58:61], v[142:145], v[214:217], v[58:61]
	v_mfma_f32_16x16x32_bf16 v[46:49], v[130:133], v[218:221], v[46:49]
	v_mfma_f32_16x16x32_bf16 v[46:49], v[134:137], v[222:225], v[46:49]
	v_mfma_f32_16x16x32_bf16 v[42:45], v[138:141], v[218:221], v[42:45]
	v_mfma_f32_16x16x32_bf16 v[42:45], v[142:145], v[222:225], v[42:45]
	v_mfma_f32_16x16x32_bf16 v[30:33], v[130:133], v[226:229], v[30:33]
	v_mfma_f32_16x16x32_bf16 v[30:33], v[134:137], v[230:233], v[30:33]
	v_mfma_f32_16x16x32_bf16 v[26:29], v[138:141], v[226:229], v[26:29]
	v_mfma_f32_16x16x32_bf16 v[26:29], v[142:145], v[230:233], v[26:29]
	v_mfma_f32_16x16x32_bf16 v[14:17], v[130:133], v[234:237], v[14:17]
	v_mfma_f32_16x16x32_bf16 v[14:17], v[134:137], v[238:241], v[14:17]
	v_mfma_f32_16x16x32_bf16 v[10:13], v[138:141], v[234:237], v[10:13]
	v_mfma_f32_16x16x32_bf16 v[10:13], v[142:145], v[238:241], v[10:13]
	v_mfma_f32_16x16x32_bf16 v[54:57], v[170:173], v[210:213], v[54:57]
	v_mfma_f32_16x16x32_bf16 v[54:57], v[174:177], v[214:217], v[54:57]
	v_mfma_f32_16x16x32_bf16 v[50:53], v[202:205], v[210:213], v[50:53]
	v_mfma_f32_16x16x32_bf16 v[50:53], v[206:209], v[214:217], v[50:53]
	v_mfma_f32_16x16x32_bf16 v[38:41], v[170:173], v[218:221], v[38:41]
	v_mfma_f32_16x16x32_bf16 v[38:41], v[174:177], v[222:225], v[38:41]
	v_mfma_f32_16x16x32_bf16 v[34:37], v[202:205], v[218:221], v[34:37]
	v_mfma_f32_16x16x32_bf16 v[34:37], v[206:209], v[222:225], v[34:37]
	v_mfma_f32_16x16x32_bf16 v[22:25], v[170:173], v[226:229], v[22:25]
	v_mfma_f32_16x16x32_bf16 v[22:25], v[174:177], v[230:233], v[22:25]
	v_mfma_f32_16x16x32_bf16 v[18:21], v[202:205], v[226:229], v[18:21]
	v_mfma_f32_16x16x32_bf16 v[18:21], v[206:209], v[230:233], v[18:21]
	v_mfma_f32_16x16x32_bf16 v[6:9], v[170:173], v[234:237], v[6:9]
	v_mfma_f32_16x16x32_bf16 v[6:9], v[174:177], v[238:241], v[6:9]
	v_mfma_f32_16x16x32_bf16 v[2:5], v[202:205], v[234:237], v[2:5]
	v_mfma_f32_16x16x32_bf16 v[2:5], v[206:209], v[238:241], v[2:5]
	s_barrier
	s_add_u32 s12, s12, 0x100
	s_addc_u32 s13, s13, 0
	s_add_u32 s16, s16, 0x100
	s_addc_u32 s17, s17, 0
	s_cmp_ge_u32 s42, s28
	s_mov_b32 s14, s42
	s_cbranch_scc0 .LBB0_322
	s_branch .Lk_done
.LBB0_322:
	s_add_i32 s42, s14, 2
	s_add_u32 s43, s12, 0x80
	s_addc_u32 s15, s13, 0
	s_add_i32 s75, 0, 0x10000
	s_cmp_eq_u32 s25, s14
	s_cselect_b32 s15, s55, s15
	s_cselect_b32 s14, s54, s43
	s_cselect_b32 vcc_hi, s65, s17
	s_cselect_b32 vcc_lo, s64, s16
	s_add_i32 s43, 0, 0x14000
	v_add_u32_e32 v142, s75, v199
	v_add_u32_e32 v178, s43, v199
	ds_read_b128 v[130:133], v142
	ds_read_b128 v[134:137], v142 offset:1024
	ds_read_b128 v[138:141], v142 offset:2048
	ds_read_b128 v[142:145], v142 offset:3072
	ds_read_b128 v[170:173], v178
	ds_read_b128 v[174:177], v178 offset:1024
	ds_read_b128 v[202:205], v178 offset:2048
	ds_read_b128 v[206:209], v178 offset:3072
	v_lshl_add_u64 v[178:179], s[12:13], 0, v[166:167]
	s_add_i32 m0, s56, 0xc000
	ds_read_b128 v[210:213], v201
	ds_read_b128 v[214:217], v201 offset:1024
	ds_read_b128 v[218:221], v201 offset:2048
	ds_read_b128 v[222:225], v201 offset:3072
	ds_read_b128 v[226:229], v201 offset:4096
	ds_read_b128 v[230:233], v201 offset:5120
	ds_read_b128 v[234:237], v201 offset:6144
	ds_read_b128 v[238:241], v201 offset:7168
	global_load_lds_dwordx4 v[178:179], off
	v_lshl_add_u64 v[178:179], s[12:13], 0, v[168:169]
	s_add_i32 m0, s56, 0xe000
	s_nop 0
	global_load_lds_dwordx4 v[178:179], off
	s_waitcnt vmcnt(8)
	s_waitcnt lgkmcnt(0)
	s_barrier
; #define PG8_STAGE(bufoff, gbase, voff) do { _Pragma("unroll") for (int _i = 0; _i < 2; ++_i) \
;         __builtin_amdgcn_global_load_lds((const unsigned*)((const char*)(gbase) + (voff)[_i]), (PG8_LAS unsigned*)(lds + (bufoff) + ldsw + _i * 8192), 16, 0, 0); } while (0)
; #define PG8_LDA(dst, b, h) do { _Pragma("unroll") for (int m = 0; m < 4; ++m) _Pragma("unroll") for (int k = 0; k < 2; ++k) dst[m][k] = *(const PG8_LAS bf16x8*)(lds + PG8_SA(b, h) + aoff + m * 2048 + k * 1024); } while (0)
; #define PG8_MMA(ai, bj, At, Bt) do { __builtin_amdgcn_s_setprio(1); _Pragma("unroll") for (int m = 0; m < 4; ++m) _Pragma("unroll") for (int n = 0; n < 2; ++n) _Pragma("unroll") for (int k = 0; k < 2; ++k) \
;         acc[ai][bj][m][n] = __builtin_amdgcn_mfma_f32_16x16x32_bf16(Bt[n][k], At[m][k], acc[ai][bj][m][n], 0, 0, 0); __builtin_amdgcn_s_setprio(0); } while (0)
; #define PG8_WAIT_V(n) asm volatile("s_waitcnt vmcnt(" #n ")" ::: "memory")
; #define PG8_WAIT_L(n) asm volatile("s_waitcnt lgkmcnt(" #n ")" ::: "memory")
; #define PG8_BAR __builtin_amdgcn_s_barrier()
; #define PG8_SCHED __builtin_amdgcn_sched_barrier(0)
; template <class Epi, class Sched, bool ALIGN_EPI = false, bool SP2 = false>
; __device__ __forceinline__ void gemm_phase(PG8_LAS unsigned char* lds, const Gemm g, const Sched& S, const Epi& E) {
;     ...
;             PG8_WAIT_V(8); PG8_WAIT_L(0); PG8_BAR; PG8_MMA(0, 0, At, B0); PG8_MMA(0, 1, At, B1); PG8_BAR; PG8_SCHED;
;             PG8_LDA(At, 0, 1); PG8_STAGE(PG8_SB(0, 0), b2, voffB); PG8_STAGE(PG8_SB(0, 1), b2 + hstep, voffB); PG8_STAGE(PG8_SA(0, 0), a2, voffA);
;             PG8_WAIT_V(8); PG8_WAIT_L(0); PG8_BAR; PG8_MMA(1, 0, At, B0); PG8_MMA(1, 1, At, B1); PG8_BAR; PG8_SCHED;
	s_waitcnt lgkmcnt(0)
	v_mfma_f32_16x16x32_bf16 v[126:129], v[130:133], v[210:213], v[126:129]
	v_mfma_f32_16x16x32_bf16 v[126:129], v[134:137], v[214:217], v[126:129]
	v_mfma_f32_16x16x32_bf16 v[122:125], v[138:141], v[210:213], v[122:125]
	v_mfma_f32_16x16x32_bf16 v[122:125], v[142:145], v[214:217], v[122:125]
	v_mfma_f32_16x16x32_bf16 v[110:113], v[130:133], v[218:221], v[110:113]
	v_mfma_f32_16x16x32_bf16 v[110:113], v[134:137], v[222:225], v[110:113]
	v_mfma_f32_16x16x32_bf16 v[106:109], v[138:141], v[218:221], v[106:109]
	v_mfma_f32_16x16x32_bf16 v[106:109], v[142:145], v[222:225], v[106:109]
	v_mfma_f32_16x16x32_bf16 v[94:97], v[130:133], v[226:229], v[94:97]
	v_mfma_f32_16x16x32_bf16 v[94:97], v[134:137], v[230:233], v[94:97]
	v_mfma_f32_16x16x32_bf16 v[90:93], v[138:141], v[226:229], v[90:93]
	v_mfma_f32_16x16x32_bf16 v[90:93], v[142:145], v[230:233], v[90:93]
	v_mfma_f32_16x16x32_bf16 v[78:81], v[130:133], v[234:237], v[78:81]
	v_mfma_f32_16x16x32_bf16 v[78:81], v[134:137], v[238:241], v[78:81]
	v_mfma_f32_16x16x32_bf16 v[74:77], v[138:141], v[234:237], v[74:77]
	v_mfma_f32_16x16x32_bf16 v[74:77], v[142:145], v[238:241], v[74:77]
	v_mfma_f32_16x16x32_bf16 v[118:121], v[170:173], v[210:213], v[118:121]
	v_mfma_f32_16x16x32_bf16 v[118:121], v[174:177], v[214:217], v[118:121]
	v_mfma_f32_16x16x32_bf16 v[114:117], v[202:205], v[210:213], v[114:117]
	v_mfma_f32_16x16x32_bf16 v[114:117], v[206:209], v[214:217], v[114:117]
	v_mfma_f32_16x16x32_bf16 v[102:105], v[170:173], v[218:221], v[102:105]
	v_mfma_f32_16x16x32_bf16 v[102:105], v[174:177], v[222:225], v[102:105]
	v_mfma_f32_16x16x32_bf16 v[98:101], v[202:205], v[218:221], v[98:101]
	v_mfma_f32_16x16x32_bf16 v[98:101], v[206:209], v[222:225], v[98:101]
	v_mfma_f32_16x16x32_bf16 v[86:89], v[170:173], v[226:229], v[86:89]
	v_mfma_f32_16x16x32_bf16 v[86:89], v[174:177], v[230:233], v[86:89]
	v_mfma_f32_16x16x32_bf16 v[82:85], v[202:205], v[226:229], v[82:85]
	v_mfma_f32_16x16x32_bf16 v[82:85], v[206:209], v[230:233], v[82:85]
	v_mfma_f32_16x16x32_bf16 v[70:73], v[170:173], v[234:237], v[70:73]
	v_mfma_f32_16x16x32_bf16 v[70:73], v[174:177], v[238:241], v[70:73]
	v_mfma_f32_16x16x32_bf16 v[66:69], v[202:205], v[234:237], v[66:69]
	v_mfma_f32_16x16x32_bf16 v[66:69], v[206:209], v[238:241], v[66:69]
	s_barrier
	s_add_i32 s75, s75, s23
	v_lshl_add_u64 v[178:179], vcc, 0, v[0:1]
	s_mov_b32 m0, s75
	ds_read_b128 v[210:213], v201 offset:16384
	ds_read_b128 v[214:217], v201 offset:17408
	ds_read_b128 v[218:221], v201 offset:18432
	ds_read_b128 v[222:225], v201 offset:19456
	ds_read_b128 v[226:229], v201 offset:20480
	ds_read_b128 v[230:233], v201 offset:21504
	ds_read_b128 v[234:237], v201 offset:22528
	ds_read_b128 v[238:241], v201 offset:23552
	global_load_lds_dwordx4 v[178:179], off
	s_add_i32 m0, s75, 0x2000
	v_lshl_add_u64 v[242:243], vcc, 0, v[162:163]
	s_add_u32 vcc_lo, vcc_lo, s84
	s_addc_u32 vcc_hi, vcc_hi, 0
	s_add_i32 s43, s43, s23
	global_load_lds_dwordx4 v[242:243], off
	v_lshl_add_u64 v[244:245], vcc, 0, v[0:1]
	s_mov_b32 m0, s43
	v_lshl_add_u64 v[246:247], vcc, 0, v[162:163]
	global_load_lds_dwordx4 v[244:245], off
	s_add_i32 m0, s43, 0x2000
	v_lshl_add_u64 v[248:249], s[14:15], 0, v[158:159]
	global_load_lds_dwordx4 v[246:247], off
	s_mov_b32 m0, s56
	v_lshl_add_u64 v[250:251], s[14:15], 0, v[160:161]
	global_load_lds_dwordx4 v[248:249], off
	s_mov_b32 m0, s82
	s_nop 0
	global_load_lds_dwordx4 v[250:251], off
	s_waitcnt vmcnt(8)
	s_waitcnt lgkmcnt(0)
	s_barrier
	s_waitcnt lgkmcnt(0)
	v_mfma_f32_16x16x32_bf16 v[62:65], v[130:133], v[210:213], v[62:65]
	v_mfma_f32_16x16x32_bf16 v[62:65], v[134:137], v[214:217], v[62:65]
	v_mfma_f32_16x16x32_bf16 v[58:61], v[138:141], v[210:213], v[58:61]
	v_mfma_f32_16x16x32_bf16 v[58:61], v[142:145], v[214:217], v[58:61]
	v_mfma_f32_16x16x32_bf16 v[46:49], v[130:133], v[218:221], v[46:49]
	v_mfma_f32_16x16x32_bf16 v[46:49], v[134:137], v[222:225], v[46:49]
	v_mfma_f32_16x16x32_bf16 v[42:45], v[138:141], v[218:221], v[42:45]
	v_mfma_f32_16x16x32_bf16 v[42:45], v[142:145], v[222:225], v[42:45]
	v_mfma_f32_16x16x32_bf16 v[30:33], v[130:133], v[226:229], v[30:33]
	v_mfma_f32_16x16x32_bf16 v[30:33], v[134:137], v[230:233], v[30:33]
	v_mfma_f32_16x16x32_bf16 v[26:29], v[138:141], v[226:229], v[26:29]
	v_mfma_f32_16x16x32_bf16 v[26:29], v[142:145], v[230:233], v[26:29]
	v_mfma_f32_16x16x32_bf16 v[14:17], v[130:133], v[234:237], v[14:17]
	v_mfma_f32_16x16x32_bf16 v[14:17], v[134:137], v[238:241], v[14:17]
	v_mfma_f32_16x16x32_bf16 v[10:13], v[138:141], v[234:237], v[10:13]
	v_mfma_f32_16x16x32_bf16 v[10:13], v[142:145], v[238:241], v[10:13]
	v_mfma_f32_16x16x32_bf16 v[54:57], v[170:173], v[210:213], v[54:57]
	v_mfma_f32_16x16x32_bf16 v[54:57], v[174:177], v[214:217], v[54:57]
	v_mfma_f32_16x16x32_bf16 v[50:53], v[202:205], v[210:213], v[50:53]
	v_mfma_f32_16x16x32_bf16 v[50:53], v[206:209], v[214:217], v[50:53]
	v_mfma_f32_16x16x32_bf16 v[38:41], v[170:173], v[218:221], v[38:41]
	v_mfma_f32_16x16x32_bf16 v[38:41], v[174:177], v[222:225], v[38:41]
	v_mfma_f32_16x16x32_bf16 v[34:37], v[202:205], v[218:221], v[34:37]
	v_mfma_f32_16x16x32_bf16 v[34:37], v[206:209], v[222:225], v[34:37]
	v_mfma_f32_16x16x32_bf16 v[22:25], v[170:173], v[226:229], v[22:25]
	v_mfma_f32_16x16x32_bf16 v[22:25], v[174:177], v[230:233], v[22:25]
	v_mfma_f32_16x16x32_bf16 v[18:21], v[202:205], v[226:229], v[18:21]
	v_mfma_f32_16x16x32_bf16 v[18:21], v[206:209], v[230:233], v[18:21]
	v_mfma_f32_16x16x32_bf16 v[6:9], v[170:173], v[234:237], v[6:9]
	v_mfma_f32_16x16x32_bf16 v[6:9], v[174:177], v[238:241], v[6:9]
	v_mfma_f32_16x16x32_bf16 v[2:5], v[202:205], v[234:237], v[2:5]
	v_mfma_f32_16x16x32_bf16 v[2:5], v[206:209], v[238:241], v[2:5]
	s_barrier
; #define PG8_STAGE(bufoff, gbase, voff) do { _Pragma("unroll") for (int _i = 0; _i < 2; ++_i) \
;         __builtin_amdgcn_global_load_lds((const unsigned*)((const char*)(gbase) + (voff)[_i]), (PG8_LAS unsigned*)(lds + (bufoff) + ldsw + _i * 8192), 16, 0, 0); } while (0)
; #define PG8_LDA(dst, b, h) do { _Pragma("unroll") for (int m = 0; m < 4; ++m) _Pragma("unroll") for (int k = 0; k < 2; ++k) dst[m][k] = *(const PG8_LAS bf16x8*)(lds + PG8_SA(b, h) + aoff + m * 2048 + k * 1024); } while (0)
; #define PG8_LDB(dst, b, h) do { _Pragma("unroll") for (int n = 0; n < 2; ++n) _Pragma("unroll") for (int k = 0; k < 2; ++k) dst[n][k] = *(const PG8_LAS bf16x8*)(lds + PG8_SB(b, h) + boff + n * 2048 + k * 1024); } while (0)
; #define PG8_MMA(ai, bj, At, Bt) do { __builtin_amdgcn_s_setprio(1); _Pragma("unroll") for (int m = 0; m < 4; ++m) _Pragma("unroll") for (int n = 0; n < 2; ++n) _Pragma("unroll") for (int k = 0; k < 2; ++k) \
;         acc[ai][bj][m][n] = __builtin_amdgcn_mfma_f32_16x16x32_bf16(Bt[n][k], At[m][k], acc[ai][bj][m][n], 0, 0, 0); __builtin_amdgcn_s_setprio(0); } while (0)
; #define PG8_WAIT_V(n) asm volatile("s_waitcnt vmcnt(" #n ")" ::: "memory")
; #define PG8_WAIT_L(n) asm volatile("s_waitcnt lgkmcnt(" #n ")" ::: "memory")
; #define PG8_BAR __builtin_amdgcn_s_barrier()
; #define PG8_SCHED __builtin_amdgcn_sched_barrier(0)
; template <class Epi, class Sched, bool ALIGN_EPI = false, bool SP2 = false>
; __device__ __forceinline__ void gemm_phase(PG8_LAS unsigned char* lds, const Gemm g, const Sched& S, const Epi& E) {
;     ...
;             PG8_LDB(B0, 1, 0); PG8_LDB(B1, 1, 1); PG8_SCHED; PG8_LDA(At, 1, 0); PG8_STAGE(PG8_SA(0, 1), a2 + hstep, voffA);
;             PG8_WAIT_V(8); PG8_WAIT_L(0); PG8_BAR; PG8_MMA(0, 0, At, B0); PG8_MMA(0, 1, At, B1); PG8_BAR; PG8_SCHED;
;             PG8_LDA(At, 1, 1); PG8_STAGE(PG8_SB(1, 0), b3, voffB); PG8_STAGE(PG8_SB(1, 1), b3 + hstep, voffB); PG8_STAGE(PG8_SA(1, 0), a3, voffA);
;             PG8_WAIT_V(8); PG8_WAIT_L(0); PG8_BAR; PG8_MMA(1, 0, At, B0); PG8_MMA(1, 1, At, B1); PG8_BAR; PG8_SCHED;
	s_add_i32 s43, 0, 0x18000
	s_add_i32 s75, 0, 0x1c000
	v_add_u32_e32 v142, s43, v199
	v_add_u32_e32 v206, s75, v199
	ds_read_b128 v[130:133], v142
	ds_read_b128 v[134:137], v142 offset:1024
	ds_read_b128 v[138:141], v142 offset:2048
	ds_read_b128 v[142:145], v142 offset:3072
	ds_read_b128 v[170:173], v206
	ds_read_b128 v[174:177], v206 offset:1024
	ds_read_b128 v[202:205], v206 offset:2048
	ds_read_b128 v[206:209], v206 offset:3072
	s_add_u32 s14, s14, s84
	s_addc_u32 s15, s15, 0
	s_mov_b32 m0, s83
	v_lshl_add_u64 v[252:253], s[14:15], 0, v[158:159]
	ds_read_b128 v[210:213], v201 offset:32768
	ds_read_b128 v[214:217], v201 offset:33792
	ds_read_b128 v[218:221], v201 offset:34816
	ds_read_b128 v[222:225], v201 offset:35840
	ds_read_b128 v[226:229], v201 offset:36864
	ds_read_b128 v[230:233], v201 offset:37888
	ds_read_b128 v[234:237], v201 offset:38912
	ds_read_b128 v[238:241], v201 offset:39936
	global_load_lds_dwordx4 v[252:253], off
	v_lshl_add_u64 v[252:253], s[14:15], 0, v[160:161]
	s_mov_b32 m0, s24
	s_nop 0
	global_load_lds_dwordx4 v[252:253], off
	s_waitcnt vmcnt(8)
	s_waitcnt lgkmcnt(0)
	s_barrier
	s_waitcnt lgkmcnt(0)
	v_mfma_f32_16x16x32_bf16 v[126:129], v[130:133], v[210:213], v[126:129]
	v_mfma_f32_16x16x32_bf16 v[126:129], v[134:137], v[214:217], v[126:129]
	v_mfma_f32_16x16x32_bf16 v[122:125], v[138:141], v[210:213], v[122:125]
	v_mfma_f32_16x16x32_bf16 v[122:125], v[142:145], v[214:217], v[122:125]
	v_mfma_f32_16x16x32_bf16 v[110:113], v[130:133], v[218:221], v[110:113]
	v_mfma_f32_16x16x32_bf16 v[110:113], v[134:137], v[222:225], v[110:113]
	v_mfma_f32_16x16x32_bf16 v[106:109], v[138:141], v[218:221], v[106:109]
	v_mfma_f32_16x16x32_bf16 v[106:109], v[142:145], v[222:225], v[106:109]
	v_mfma_f32_16x16x32_bf16 v[94:97], v[130:133], v[226:229], v[94:97]
	v_mfma_f32_16x16x32_bf16 v[94:97], v[134:137], v[230:233], v[94:97]
	v_mfma_f32_16x16x32_bf16 v[90:93], v[138:141], v[226:229], v[90:93]
	v_mfma_f32_16x16x32_bf16 v[90:93], v[142:145], v[230:233], v[90:93]
	v_mfma_f32_16x16x32_bf16 v[78:81], v[130:133], v[234:237], v[78:81]
	v_mfma_f32_16x16x32_bf16 v[78:81], v[134:137], v[238:241], v[78:81]
	v_mfma_f32_16x16x32_bf16 v[74:77], v[138:141], v[234:237], v[74:77]
	v_mfma_f32_16x16x32_bf16 v[74:77], v[142:145], v[238:241], v[74:77]
	v_mfma_f32_16x16x32_bf16 v[118:121], v[170:173], v[210:213], v[118:121]
	v_mfma_f32_16x16x32_bf16 v[118:121], v[174:177], v[214:217], v[118:121]
	v_mfma_f32_16x16x32_bf16 v[114:117], v[202:205], v[210:213], v[114:117]
	v_mfma_f32_16x16x32_bf16 v[114:117], v[206:209], v[214:217], v[114:117]
	v_mfma_f32_16x16x32_bf16 v[102:105], v[170:173], v[218:221], v[102:105]
	v_mfma_f32_16x16x32_bf16 v[102:105], v[174:177], v[222:225], v[102:105]
	v_mfma_f32_16x16x32_bf16 v[98:101], v[202:205], v[218:221], v[98:101]
	v_mfma_f32_16x16x32_bf16 v[98:101], v[206:209], v[222:225], v[98:101]
	v_mfma_f32_16x16x32_bf16 v[86:89], v[170:173], v[226:229], v[86:89]
	v_mfma_f32_16x16x32_bf16 v[86:89], v[174:177], v[230:233], v[86:89]
	v_mfma_f32_16x16x32_bf16 v[82:85], v[202:205], v[226:229], v[82:85]
	v_mfma_f32_16x16x32_bf16 v[82:85], v[206:209], v[230:233], v[82:85]
	v_mfma_f32_16x16x32_bf16 v[70:73], v[170:173], v[234:237], v[70:73]
	v_mfma_f32_16x16x32_bf16 v[70:73], v[174:177], v[238:241], v[70:73]
	v_mfma_f32_16x16x32_bf16 v[66:69], v[202:205], v[234:237], v[66:69]
	v_mfma_f32_16x16x32_bf16 v[66:69], v[206:209], v[238:241], v[66:69]
	s_barrier
	s_add_i32 s14, s43, s23
	v_lshl_add_u64 v[178:179], v[178:179], 0, s[94:95]
	s_mov_b32 m0, s14
	ds_read_b128 v[210:213], v201 offset:49152
	ds_read_b128 v[214:217], v201 offset:50176
	ds_read_b128 v[218:221], v201 offset:51200
	ds_read_b128 v[222:225], v201 offset:52224
	ds_read_b128 v[226:229], v201 offset:53248
	ds_read_b128 v[230:233], v201 offset:54272
	ds_read_b128 v[234:237], v201 offset:55296
	ds_read_b128 v[238:241], v201 offset:56320
	global_load_lds_dwordx4 v[178:179], off
	v_lshl_add_u64 v[178:179], v[242:243], 0, s[94:95]
	s_add_i32 m0, s14, 0x2000
	s_add_i32 s14, s75, s23
	global_load_lds_dwordx4 v[178:179], off
	v_lshl_add_u64 v[178:179], v[244:245], 0, s[94:95]
	s_mov_b32 m0, s14
	s_nop 0
	global_load_lds_dwordx4 v[178:179], off
	v_lshl_add_u64 v[178:179], v[246:247], 0, s[94:95]
	s_add_i32 m0, s14, 0x2000
	s_nop 0
	global_load_lds_dwordx4 v[178:179], off
	v_lshl_add_u64 v[178:179], v[248:249], 0, s[94:95]
	s_mov_b32 m0, s63
	s_nop 0
	global_load_lds_dwordx4 v[178:179], off
	v_lshl_add_u64 v[178:179], v[250:251], 0, s[94:95]
	s_mov_b32 m0, s70
	s_nop 0
	global_load_lds_dwordx4 v[178:179], off
	s_waitcnt vmcnt(8)
	s_waitcnt lgkmcnt(0)
	s_barrier
	s_waitcnt lgkmcnt(0)
	v_mfma_f32_16x16x32_bf16 v[62:65], v[130:133], v[210:213], v[62:65]
	v_mfma_f32_16x16x32_bf16 v[62:65], v[134:137], v[214:217], v[62:65]
	v_mfma_f32_16x16x32_bf16 v[58:61], v[138:141], v[210:213], v[58:61]
	v_mfma_f32_16x16x32_bf16 v[58:61], v[142:145], v[214:217], v[58:61]
	v_mfma_f32_16x16x32_bf16 v[46:49], v[130:133], v[218:221], v[46:49]
	v_mfma_f32_16x16x32_bf16 v[46:49], v[134:137], v[222:225], v[46:49]
	v_mfma_f32_16x16x32_bf16 v[42:45], v[138:141], v[218:221], v[42:45]
	v_mfma_f32_16x16x32_bf16 v[42:45], v[142:145], v[222:225], v[42:45]
	v_mfma_f32_16x16x32_bf16 v[30:33], v[130:133], v[226:229], v[30:33]
	v_mfma_f32_16x16x32_bf16 v[30:33], v[134:137], v[230:233], v[30:33]
	v_mfma_f32_16x16x32_bf16 v[26:29], v[138:141], v[226:229], v[26:29]
	v_mfma_f32_16x16x32_bf16 v[26:29], v[142:145], v[230:233], v[26:29]
	v_mfma_f32_16x16x32_bf16 v[14:17], v[130:133], v[234:237], v[14:17]
	v_mfma_f32_16x16x32_bf16 v[14:17], v[134:137], v[238:241], v[14:17]
	v_mfma_f32_16x16x32_bf16 v[10:13], v[138:141], v[234:237], v[10:13]
	v_mfma_f32_16x16x32_bf16 v[10:13], v[142:145], v[238:241], v[10:13]
	v_mfma_f32_16x16x32_bf16 v[54:57], v[170:173], v[210:213], v[54:57]
	v_mfma_f32_16x16x32_bf16 v[54:57], v[174:177], v[214:217], v[54:57]
	v_mfma_f32_16x16x32_bf16 v[50:53], v[202:205], v[210:213], v[50:53]
	v_mfma_f32_16x16x32_bf16 v[50:53], v[206:209], v[214:217], v[50:53]
	v_mfma_f32_16x16x32_bf16 v[38:41], v[170:173], v[218:221], v[38:41]
	v_mfma_f32_16x16x32_bf16 v[38:41], v[174:177], v[222:225], v[38:41]
	v_mfma_f32_16x16x32_bf16 v[34:37], v[202:205], v[218:221], v[34:37]
	v_mfma_f32_16x16x32_bf16 v[34:37], v[206:209], v[222:225], v[34:37]
	v_mfma_f32_16x16x32_bf16 v[22:25], v[170:173], v[226:229], v[22:25]
	v_mfma_f32_16x16x32_bf16 v[22:25], v[174:177], v[230:233], v[22:25]
	v_mfma_f32_16x16x32_bf16 v[18:21], v[202:205], v[226:229], v[18:21]
	v_mfma_f32_16x16x32_bf16 v[18:21], v[206:209], v[230:233], v[18:21]
	v_mfma_f32_16x16x32_bf16 v[6:9], v[170:173], v[234:237], v[6:9]
	v_mfma_f32_16x16x32_bf16 v[6:9], v[174:177], v[238:241], v[6:9]
	v_mfma_f32_16x16x32_bf16 v[2:5], v[202:205], v[234:237], v[2:5]
	v_mfma_f32_16x16x32_bf16 v[2:5], v[206:209], v[238:241], v[2:5]
	s_barrier
	s_add_u32 s12, s12, 0x100
	s_addc_u32 s13, s13, 0
	s_add_u32 s16, s16, 0x100
	s_addc_u32 s17, s17, 0
	s_cmp_ge_u32 s42, s28
	s_mov_b32 s14, s42
	s_cbranch_scc0 .LBB0_322
